# nt hint on streaming x (f32 input) loads in the two residual/norm row phases and on the final output stores
# speedup vs baseline: 1.0111x; 1.0064x over previous
.LBB0_113:
	s_ashr_i32 s15, s14, 31
	s_add_i32 s0, s14, 1
	s_ashr_i32 s20, s17, 11
	s_add_i32 s4, s14, 2
	s_add_i32 s8, s14, 3
	s_lshl_b64 s[18:19], s[14:15], 12
	s_ashr_i32 s1, s0, 31
	s_mul_i32 s20, s20, 9
	s_ashr_i32 s5, s4, 31
	s_ashr_i32 s9, s8, 31
	v_lshl_add_u64 v[0:1], v[68:69], 0, s[18:19]
	s_lshl_b64 s[18:19], s[0:1], 12
	s_ashr_i32 s21, s20, 31
	s_lshl_b64 s[26:27], s[4:5], 12
	s_lshl_b64 s[28:29], s[8:9], 12
	v_lshl_add_u64 v[76:77], v[68:69], 0, s[18:19]
	s_lshl_b64 s[18:19], s[20:21], 12
	global_load_dwordx4 v[64:67], v[72:73], off
	global_load_dwordx4 v[36:39], v[0:1], off nt
	global_load_dwordx4 v[20:23], v[0:1], off offset:1024 nt
	global_load_dwordx4 v[16:19], v[0:1], off offset:2048 nt
	s_nop 0
	global_load_dwordx4 v[0:3], v[0:1], off offset:3072 nt
	s_add_u32 s18, s2, s18
	s_addc_u32 s19, s3, s19
	s_add_u32 s20, s18, 0x1000
	v_lshl_add_u64 v[78:79], v[68:69], 0, s[26:27]
	v_lshl_add_u64 v[80:81], v[68:69], 0, s[28:29]
	global_load_dwordx4 v[52:55], v[76:77], off nt
	global_load_dwordx4 v[48:51], v[76:77], off offset:1024 nt
	global_load_dwordx4 v[56:59], v[78:79], off nt
	global_load_dwordx4 v[44:47], v[78:79], off offset:1024 nt
	global_load_dwordx4 v[60:63], v[80:81], off nt
	global_load_dwordx4 v[40:43], v[80:81], off offset:1024 nt
	global_load_dwordx4 v[24:27], v[76:77], off offset:2048 nt
	global_load_dwordx4 v[4:7], v[76:77], off offset:3072 nt
	global_load_dwordx4 v[28:31], v[78:79], off offset:2048 nt
	global_load_dwordx4 v[8:11], v[78:79], off offset:3072 nt
	global_load_dwordx4 v[32:35], v[80:81], off offset:2048 nt
	global_load_dwordx4 v[12:15], v[80:81], off offset:3072 nt
	s_addc_u32 s21, s19, 0
	global_load_dwordx4 v[94:97], v90, s[20:21]
	global_load_dwordx4 v[98:101], v90, s[18:19]
	s_lshl_b64 s[8:9], s[8:9], 11
	s_lshl_b64 s[0:1], s[0:1], 11
	s_lshl_b64 s[4:5], s[4:5], 11
	v_lshl_add_u64 v[82:83], v[70:71], 0, s[8:9]
	v_lshl_add_u64 v[78:79], v[70:71], 0, s[0:1]
	v_lshl_add_u64 v[80:81], v[70:71], 0, s[4:5]
	s_lshl_b64 s[26:27], s[14:15], 11
	v_lshl_add_u64 v[76:77], v[70:71], 0, s[26:27]
	s_add_i32 s14, s14, s23
	global_load_dwordx4 v[164:167], v91, s[20:21]
	global_load_dwordx4 v[168:171], v[72:73], off offset:1024
	global_load_dwordx4 v[172:175], v90, s[18:19] offset:1024
	global_load_dwordx4 v[176:179], v92, s[20:21]
	global_load_dwordx4 v[180:183], v[72:73], off offset:2048
	global_load_dwordx4 v[184:187], v90, s[18:19] offset:2048
	global_load_dwordx4 v[188:191], v93, s[20:21]
	global_load_dwordx4 v[192:195], v[72:73], off offset:3072
	global_load_dwordx4 v[196:199], v90, s[18:19] offset:3072
	s_waitcnt vmcnt(22)
	v_pk_mul_f32 v[116:117], v[52:53], v[52:53]
	s_waitcnt vmcnt(21)
	v_pk_mul_f32 v[118:119], v[50:51], v[50:51]
	v_pk_mul_f32 v[102:103], v[38:39], v[38:39]
	v_pk_mul_f32 v[104:105], v[36:37], v[36:37]
	v_pk_mul_f32 v[106:107], v[22:23], v[22:23]
	v_pk_mul_f32 v[108:109], v[20:21], v[20:21]
	v_mul_f32_e32 v110, v17, v17
	v_mul_f32_e32 v112, v19, v19
	v_pk_mov_b32 v[114:115], v[104:105], v[102:103] op_sel:[1,0]
	v_mov_b32_e32 v105, v103
	v_pk_mov_b32 v[102:103], v[108:109], v[106:107] op_sel:[1,0]
	v_mov_b32_e32 v109, v107
	v_pk_mul_f32 v[106:107], v[54:55], v[54:55]
	v_pk_mul_f32 v[120:121], v[48:49], v[48:49]
	v_mul_f32_e32 v139, v2, v2
	v_mul_f32_e32 v141, v3, v3
	s_waitcnt vmcnt(20)
	v_pk_mul_f32 v[122:123], v[58:59], v[58:59]
	v_pk_mul_f32 v[124:125], v[56:57], v[56:57]
	s_waitcnt vmcnt(19)
	v_pk_mul_f32 v[126:127], v[46:47], v[46:47]
	v_pk_mul_f32 v[128:129], v[44:45], v[44:45]
	s_waitcnt vmcnt(18)
	v_pk_mul_f32 v[130:131], v[62:63], v[62:63]
	v_pk_mul_f32 v[132:133], v[60:61], v[60:61]
	s_waitcnt vmcnt(17)
	v_pk_mul_f32 v[134:135], v[42:43], v[42:43]
	v_pk_mul_f32 v[136:137], v[40:41], v[40:41]
	v_pk_fma_f32 v[110:111], v[16:17], v[16:17], v[110:111] op_sel_hi:[1,1,0]
	v_pk_fma_f32 v[112:113], v[18:19], v[18:19], v[112:113] op_sel_hi:[1,1,0]
	v_pk_add_f32 v[102:103], v[102:103], v[108:109]
	v_pk_mov_b32 v[108:109], v[116:117], v[106:107] op_sel:[1,0]
	v_mov_b32_e32 v117, v107
	v_pk_mov_b32 v[106:107], v[120:121], v[118:119] op_sel:[1,0]
	v_mov_b32_e32 v121, v119
	s_waitcnt vmcnt(16)
	v_mul_f32_e32 v140, v25, v25
	v_mul_f32_e32 v142, v27, v27
	v_pk_add_f32 v[104:105], v[114:115], v[104:105]
	v_pk_mov_b32 v[114:115], v[124:125], v[122:123] op_sel:[1,0]
	v_mov_b32_e32 v125, v123
	v_pk_mov_b32 v[118:119], v[128:129], v[126:127] op_sel:[1,0]
	v_mov_b32_e32 v129, v127
	v_pk_mov_b32 v[122:123], v[132:133], v[130:131] op_sel:[1,0]
	v_mov_b32_e32 v133, v131
	v_pk_mov_b32 v[126:127], v[136:137], v[134:135] op_sel:[1,0]
	v_mov_b32_e32 v137, v135
	v_mov_b32_e32 v111, v139
	v_mov_b32_e32 v113, v141
	v_pk_add_f32 v[108:109], v[108:109], v[116:117]
	v_pk_add_f32 v[106:107], v[106:107], v[120:121]
	v_mul_f32_e32 v149, v0, v0
	v_mul_f32_e32 v151, v1, v1
	s_waitcnt vmcnt(15)
	v_mul_f32_e32 v152, v6, v6
	v_mul_f32_e32 v153, v7, v7
	s_waitcnt vmcnt(14)
	v_mul_f32_e32 v144, v29, v29
	v_mul_f32_e32 v146, v31, v31
	s_waitcnt vmcnt(12)
	v_mul_f32_e32 v148, v33, v33
	v_mul_f32_e32 v150, v35, v35
	v_mul_f32_e32 v158, v4, v4
	v_mul_f32_e32 v159, v5, v5
	v_pk_fma_f32 v[130:131], v[24:25], v[24:25], v[140:141] op_sel_hi:[1,1,0]
	v_pk_fma_f32 v[134:135], v[26:27], v[26:27], v[142:143] op_sel_hi:[1,1,0]
	v_pk_add_f32 v[110:111], v[110:111], v[112:113]
	v_pk_add_f32 v[112:113], v[114:115], v[124:125]
	v_pk_add_f32 v[114:115], v[118:119], v[128:129]
	v_pk_add_f32 v[116:117], v[122:123], v[132:133]
	v_pk_add_f32 v[118:119], v[126:127], v[136:137]
	v_pk_add_f32 v[104:105], v[104:105], v[104:105] op_sel:[0,1] op_sel_hi:[1,0]
	v_pk_add_f32 v[102:103], v[102:103], v[102:103] op_sel:[0,1] op_sel_hi:[1,0]
	v_pk_add_f32 v[108:109], v[108:109], v[108:109] op_sel:[0,1] op_sel_hi:[1,0]
	v_pk_add_f32 v[106:107], v[106:107], v[106:107] op_sel:[0,1] op_sel_hi:[1,0]
	v_mul_f32_e32 v154, v10, v10
	v_mul_f32_e32 v155, v11, v11
	s_waitcnt vmcnt(11)
	v_mul_f32_e32 v156, v14, v14
	v_mul_f32_e32 v157, v15, v15
	v_mul_f32_e32 v160, v8, v8
	v_mul_f32_e32 v161, v9, v9
	v_mul_f32_e32 v162, v12, v12
	v_mul_f32_e32 v163, v13, v13
	v_pk_fma_f32 v[140:141], v[28:29], v[28:29], v[144:145] op_sel_hi:[1,1,0]
	v_pk_fma_f32 v[142:143], v[30:31], v[30:31], v[146:147] op_sel_hi:[1,1,0]
	v_pk_fma_f32 v[144:145], v[32:33], v[32:33], v[148:149] op_sel_hi:[1,1,0]
	v_pk_fma_f32 v[146:147], v[34:35], v[34:35], v[150:151] op_sel_hi:[1,1,0]
	v_mov_b32_e32 v131, v152
	v_mov_b32_e32 v135, v153
	v_mov_b32_e32 v105, v149
	v_mov_b32_e32 v103, v151
	v_pk_add_f32 v[112:113], v[112:113], v[112:113] op_sel:[0,1] op_sel_hi:[1,0]
	v_pk_add_f32 v[114:115], v[114:115], v[114:115] op_sel:[0,1] op_sel_hi:[1,0]
	v_pk_add_f32 v[116:117], v[116:117], v[116:117] op_sel:[0,1] op_sel_hi:[1,0]
	v_pk_add_f32 v[118:119], v[118:119], v[118:119] op_sel:[0,1] op_sel_hi:[1,0]
	s_waitcnt vmcnt(10)
	v_pk_add_f32 v[96:97], v[96:97], 1.0 op_sel_hi:[1,0]
	v_mov_b32_e32 v109, v158
	v_mov_b32_e32 v107, v159
	v_mov_b32_e32 v141, v154
	v_mov_b32_e32 v143, v155
	v_mov_b32_e32 v145, v156
	v_mov_b32_e32 v147, v157
	v_pk_add_f32 v[120:121], v[130:131], v[134:135]
	v_pk_add_f32 v[94:95], v[94:95], 1.0 op_sel_hi:[1,0]
	v_pk_add_f32 v[102:103], v[104:105], v[102:103]
	v_mov_b32_e32 v113, v160
	v_mov_b32_e32 v115, v161
	v_mov_b32_e32 v117, v162
	v_mov_b32_e32 v119, v163
	v_pk_mul_f32 v[66:67], v[66:67], v[96:97]
	v_pk_add_f32 v[96:97], v[108:109], v[106:107]
	v_pk_add_f32 v[122:123], v[140:141], v[142:143]
	v_pk_add_f32 v[124:125], v[144:145], v[146:147]
	v_pk_mul_f32 v[64:65], v[64:65], v[94:95]
	v_pk_add_f32 v[94:95], v[102:103], v[110:111]
	v_pk_add_f32 v[102:103], v[112:113], v[114:115]
	v_pk_add_f32 v[104:105], v[116:117], v[118:119]
	v_pk_add_f32 v[96:97], v[96:97], v[120:121]
	v_pk_add_f32 v[102:103], v[102:103], v[122:123]
	v_pk_add_f32 v[104:105], v[104:105], v[124:125]
	v_mov_b32_e32 v107, v94
	v_mov_b32_e32 v106, v96
	v_mov_b32_e32 v94, v97
	v_mov_b32_e32 v96, v104
	v_mov_b32_e32 v97, v102
	v_mov_b32_e32 v102, v105
	v_pk_add_f32 v[94:95], v[106:107], v[94:95]
	v_pk_add_f32 v[96:97], v[96:97], v[102:103]
	ds_bpermute_b32 v103, v84, v95
	ds_bpermute_b32 v102, v84, v94
	ds_bpermute_b32 v105, v84, v97
	ds_bpermute_b32 v104, v84, v96
	s_waitcnt lgkmcnt(2)
	v_pk_add_f32 v[94:95], v[94:95], v[102:103]
	ds_bpermute_b32 v103, v85, v95
	s_waitcnt lgkmcnt(1)
	v_pk_add_f32 v[96:97], v[96:97], v[104:105]
	ds_bpermute_b32 v102, v85, v94
	ds_bpermute_b32 v105, v85, v97
	ds_bpermute_b32 v104, v85, v96
	s_waitcnt lgkmcnt(2)
	v_pk_add_f32 v[94:95], v[94:95], v[102:103]
	ds_bpermute_b32 v103, v86, v95
	s_waitcnt lgkmcnt(1)
	v_pk_add_f32 v[96:97], v[96:97], v[104:105]
	ds_bpermute_b32 v102, v86, v94
	ds_bpermute_b32 v105, v86, v97
	ds_bpermute_b32 v104, v86, v96
	s_waitcnt lgkmcnt(2)
	v_pk_add_f32 v[94:95], v[94:95], v[102:103]
	ds_bpermute_b32 v103, v87, v95
	s_waitcnt lgkmcnt(1)
	v_pk_add_f32 v[96:97], v[96:97], v[104:105]
	ds_bpermute_b32 v102, v87, v94
	ds_bpermute_b32 v105, v87, v97
	ds_bpermute_b32 v104, v87, v96
	s_waitcnt lgkmcnt(2)
	v_pk_add_f32 v[94:95], v[94:95], v[102:103]
	ds_bpermute_b32 v103, v88, v95
	s_waitcnt lgkmcnt(1)
	v_pk_add_f32 v[96:97], v[96:97], v[104:105]
	ds_bpermute_b32 v102, v88, v94
	ds_bpermute_b32 v105, v88, v97
	ds_bpermute_b32 v104, v88, v96
	s_waitcnt lgkmcnt(2)
	v_pk_add_f32 v[94:95], v[94:95], v[102:103]
	ds_bpermute_b32 v103, v89, v95
	s_waitcnt lgkmcnt(1)
	v_pk_add_f32 v[96:97], v[96:97], v[104:105]
	ds_bpermute_b32 v102, v89, v94
	ds_bpermute_b32 v105, v89, v97
	ds_bpermute_b32 v104, v89, v96
	s_waitcnt lgkmcnt(2)
	v_pk_add_f32 v[94:95], v[94:95], v[102:103]
	s_nop 0
	v_pk_fma_f32 v[94:95], v[94:95], s[16:17], v[74:75] op_sel_hi:[1,0,0]
	s_waitcnt lgkmcnt(0)
	v_pk_add_f32 v[96:97], v[96:97], v[104:105]
	v_mul_f32_e32 v103, 0x4b800000, v95
	v_pk_fma_f32 v[96:97], v[96:97], s[16:17], v[74:75] op_sel_hi:[1,0,0]
	v_cmp_gt_f32_e64 s[8:9], s24, v95
	v_mul_f32_e32 v102, 0x4b800000, v94
	v_cmp_gt_f32_e32 vcc, s24, v94
	v_mul_f32_e32 v104, 0x4b800000, v96
	v_cmp_gt_f32_e64 s[0:1], s24, v96
	v_mul_f32_e32 v105, 0x4b800000, v97
	v_cmp_gt_f32_e64 s[4:5], s24, v97
	v_cndmask_b32_e64 v95, v95, v103, s[8:9]
	v_cndmask_b32_e32 v94, v94, v102, vcc
	v_cndmask_b32_e64 v97, v97, v105, s[4:5]
	v_cndmask_b32_e64 v96, v96, v104, s[0:1]
	v_rsq_f32_e32 v95, v95
	v_rsq_f32_e32 v102, v94
	v_rsq_f32_e32 v97, v97
	v_rsq_f32_e32 v103, v96
	v_mul_f32_e32 v94, 0x45800000, v95
	v_mul_f32_e32 v96, 0x45800000, v102
	v_mul_f32_e32 v104, 0x45800000, v97
	v_mul_f32_e32 v105, 0x45800000, v103
	v_cndmask_b32_e64 v94, v95, v94, s[8:9]
	v_cndmask_b32_e32 v96, v102, v96, vcc
	v_cndmask_b32_e64 v102, v97, v104, s[4:5]
	v_cndmask_b32_e64 v104, v103, v105, s[0:1]
	v_pk_mul_f32 v[36:37], v[36:37], v[94:95] op_sel_hi:[1,0]
	v_pk_mul_f32 v[38:39], v[38:39], v[94:95] op_sel_hi:[1,0]
	v_pk_mul_f32 v[52:53], v[52:53], v[96:97] op_sel_hi:[1,0]
	v_pk_mul_f32 v[54:55], v[54:55], v[96:97] op_sel_hi:[1,0]
	v_pk_mul_f32 v[56:57], v[56:57], v[102:103] op_sel_hi:[1,0]
	v_pk_mul_f32 v[58:59], v[58:59], v[102:103] op_sel_hi:[1,0]
	v_pk_mul_f32 v[60:61], v[60:61], v[104:105] op_sel_hi:[1,0]
	v_pk_mul_f32 v[62:63], v[62:63], v[104:105] op_sel_hi:[1,0]
	s_waitcnt vmcnt(0)
	v_pk_fma_f32 v[38:39], v[38:39], v[66:67], v[100:101]
	v_pk_fma_f32 v[36:37], v[36:37], v[64:65], v[98:99]
	v_pk_fma_f32 v[54:55], v[54:55], v[66:67], v[100:101]
	v_pk_fma_f32 v[58:59], v[66:67], v[58:59], v[100:101]
	v_pk_fma_f32 v[62:63], v[66:67], v[62:63], v[100:101]
	v_pk_fma_f32 v[52:53], v[52:53], v[64:65], v[98:99]
	v_pk_fma_f32 v[56:57], v[64:65], v[56:57], v[98:99]
	v_pk_fma_f32 v[60:61], v[64:65], v[60:61], v[98:99]
	v_cvt_pk_bf16_f32 v36, v36, v37
	v_cvt_pk_bf16_f32 v37, v38, v39
	v_cvt_pk_bf16_f32 v38, v52, v53
	v_cvt_pk_bf16_f32 v39, v54, v55
	v_cvt_pk_bf16_f32 v52, v56, v57
	v_cvt_pk_bf16_f32 v53, v58, v59
	v_cvt_pk_bf16_f32 v54, v60, v61
	v_cvt_pk_bf16_f32 v55, v62, v63
	global_store_dwordx2 v[76:77], v[36:37], off
	global_store_dwordx2 v[78:79], v[38:39], off
	global_store_dwordx2 v[80:81], v[52:53], off
	global_store_dwordx2 v[82:83], v[54:55], off
	s_nop 0
	v_pk_mul_f32 v[20:21], v[20:21], v[94:95] op_sel_hi:[1,0]
	v_pk_mul_f32 v[22:23], v[22:23], v[94:95] op_sel_hi:[1,0]
	v_pk_mul_f32 v[48:49], v[48:49], v[96:97] op_sel_hi:[1,0]
	v_pk_mul_f32 v[50:51], v[50:51], v[96:97] op_sel_hi:[1,0]
	v_pk_mul_f32 v[44:45], v[44:45], v[102:103] op_sel_hi:[1,0]
	v_pk_mul_f32 v[46:47], v[46:47], v[102:103] op_sel_hi:[1,0]
	v_pk_mul_f32 v[40:41], v[40:41], v[104:105] op_sel_hi:[1,0]
	v_pk_mul_f32 v[42:43], v[42:43], v[104:105] op_sel_hi:[1,0]
	v_pk_mul_f32 v[16:17], v[16:17], v[94:95] op_sel_hi:[1,0]
	v_pk_mul_f32 v[18:19], v[18:19], v[94:95] op_sel_hi:[1,0]
	v_pk_mul_f32 v[24:25], v[24:25], v[96:97] op_sel_hi:[1,0]
	v_pk_mul_f32 v[26:27], v[26:27], v[96:97] op_sel_hi:[1,0]
	v_pk_mul_f32 v[28:29], v[28:29], v[102:103] op_sel_hi:[1,0]
	v_pk_mul_f32 v[30:31], v[30:31], v[102:103] op_sel_hi:[1,0]
	v_pk_mul_f32 v[32:33], v[32:33], v[104:105] op_sel_hi:[1,0]
	v_pk_mul_f32 v[34:35], v[34:35], v[104:105] op_sel_hi:[1,0]
	v_pk_mul_f32 v[0:1], v[0:1], v[94:95] op_sel_hi:[1,0]
	v_pk_mul_f32 v[2:3], v[2:3], v[94:95] op_sel_hi:[1,0]
	s_add_i32 s17, s17, s22
	v_pk_mul_f32 v[4:5], v[4:5], v[96:97] op_sel_hi:[1,0]
	v_pk_mul_f32 v[6:7], v[6:7], v[96:97] op_sel_hi:[1,0]
	v_pk_mul_f32 v[8:9], v[8:9], v[102:103] op_sel_hi:[1,0]
	v_pk_mul_f32 v[10:11], v[10:11], v[102:103] op_sel_hi:[1,0]
	v_pk_mul_f32 v[12:13], v[12:13], v[104:105] op_sel_hi:[1,0]
	v_pk_mul_f32 v[14:15], v[14:15], v[104:105] op_sel_hi:[1,0]
	s_cmpk_lt_i32 s17, 0x4000
	v_pk_add_f32 v[38:39], v[166:167], 1.0 op_sel_hi:[1,0]
	v_pk_add_f32 v[36:37], v[164:165], 1.0 op_sel_hi:[1,0]
	v_pk_mul_f32 v[38:39], v[170:171], v[38:39]
	v_pk_mul_f32 v[36:37], v[168:169], v[36:37]
	v_pk_fma_f32 v[22:23], v[22:23], v[38:39], v[174:175]
	v_pk_fma_f32 v[20:21], v[20:21], v[36:37], v[172:173]
	v_pk_fma_f32 v[50:51], v[50:51], v[38:39], v[174:175]
	v_pk_fma_f32 v[48:49], v[48:49], v[36:37], v[172:173]
	v_pk_fma_f32 v[46:47], v[46:47], v[38:39], v[174:175]
	v_pk_fma_f32 v[44:45], v[44:45], v[36:37], v[172:173]
	v_pk_fma_f32 v[38:39], v[38:39], v[42:43], v[174:175]
	v_pk_fma_f32 v[36:37], v[36:37], v[40:41], v[172:173]
	v_cvt_pk_bf16_f32 v20, v20, v21
	v_cvt_pk_bf16_f32 v21, v22, v23
	v_cvt_pk_bf16_f32 v22, v48, v49
	v_cvt_pk_bf16_f32 v23, v50, v51
	v_cvt_pk_bf16_f32 v40, v44, v45
	v_cvt_pk_bf16_f32 v41, v46, v47
	v_cvt_pk_bf16_f32 v36, v36, v37
	v_cvt_pk_bf16_f32 v37, v38, v39
	global_store_dwordx2 v[76:77], v[20:21], off offset:512
	global_store_dwordx2 v[78:79], v[22:23], off offset:512
	global_store_dwordx2 v[80:81], v[40:41], off offset:512
	global_store_dwordx2 v[82:83], v[36:37], off offset:512
	s_nop 0
	v_pk_add_f32 v[22:23], v[178:179], 1.0 op_sel_hi:[1,0]
	v_pk_add_f32 v[20:21], v[176:177], 1.0 op_sel_hi:[1,0]
	v_pk_mul_f32 v[22:23], v[182:183], v[22:23]
	v_pk_mul_f32 v[20:21], v[180:181], v[20:21]
	v_pk_fma_f32 v[18:19], v[18:19], v[22:23], v[186:187]
	v_pk_fma_f32 v[16:17], v[16:17], v[20:21], v[184:185]
	v_pk_fma_f32 v[26:27], v[26:27], v[22:23], v[186:187]
	v_pk_fma_f32 v[24:25], v[24:25], v[20:21], v[184:185]
	v_pk_fma_f32 v[30:31], v[30:31], v[22:23], v[186:187]
	v_pk_fma_f32 v[28:29], v[28:29], v[20:21], v[184:185]
	v_pk_fma_f32 v[22:23], v[34:35], v[22:23], v[186:187]
	v_pk_fma_f32 v[20:21], v[32:33], v[20:21], v[184:185]
	v_cvt_pk_bf16_f32 v16, v16, v17
	v_cvt_pk_bf16_f32 v17, v18, v19
	v_cvt_pk_bf16_f32 v18, v24, v25
	v_cvt_pk_bf16_f32 v19, v26, v27
	v_cvt_pk_bf16_f32 v24, v28, v29
	v_cvt_pk_bf16_f32 v25, v30, v31
	v_cvt_pk_bf16_f32 v20, v20, v21
	v_cvt_pk_bf16_f32 v21, v22, v23
	global_store_dwordx2 v[76:77], v[16:17], off offset:1024
	global_store_dwordx2 v[78:79], v[18:19], off offset:1024
	global_store_dwordx2 v[80:81], v[24:25], off offset:1024
	global_store_dwordx2 v[82:83], v[20:21], off offset:1024
	s_nop 0
	v_pk_add_f32 v[18:19], v[190:191], 1.0 op_sel_hi:[1,0]
	v_pk_add_f32 v[16:17], v[188:189], 1.0 op_sel_hi:[1,0]
	v_pk_mul_f32 v[18:19], v[194:195], v[18:19]
	v_pk_mul_f32 v[16:17], v[192:193], v[16:17]
	v_pk_fma_f32 v[2:3], v[2:3], v[18:19], v[198:199]
	v_pk_fma_f32 v[0:1], v[0:1], v[16:17], v[196:197]
	v_pk_fma_f32 v[6:7], v[6:7], v[18:19], v[198:199]
	v_pk_fma_f32 v[4:5], v[4:5], v[16:17], v[196:197]
	v_pk_fma_f32 v[10:11], v[10:11], v[18:19], v[198:199]
	v_pk_fma_f32 v[8:9], v[8:9], v[16:17], v[196:197]
	v_pk_fma_f32 v[14:15], v[14:15], v[18:19], v[198:199]
	v_pk_fma_f32 v[12:13], v[12:13], v[16:17], v[196:197]
	v_cvt_pk_bf16_f32 v0, v0, v1
	v_cvt_pk_bf16_f32 v1, v2, v3
	v_cvt_pk_bf16_f32 v2, v4, v5
	v_cvt_pk_bf16_f32 v3, v6, v7
	v_cvt_pk_bf16_f32 v4, v8, v9
	v_cvt_pk_bf16_f32 v5, v10, v11
	v_cvt_pk_bf16_f32 v6, v12, v13
	v_cvt_pk_bf16_f32 v7, v14, v15
	global_store_dwordx2 v[76:77], v[0:1], off offset:1536
	global_store_dwordx2 v[78:79], v[2:3], off offset:1536
	global_store_dwordx2 v[80:81], v[4:5], off offset:1536
	global_store_dwordx2 v[82:83], v[6:7], off offset:1536
	s_cbranch_scc1 .LBB0_113

.LBB0_316:
	s_ashr_i32 s18, s9, 12
	s_ashr_i32 s5, s4, 31
	s_add_i32 s0, s4, 1
	s_mul_i32 s18, s18, 9
	s_lshl_b64 s[14:15], s[4:5], 11
	s_lshl_b64 s[16:17], s[4:5], 12
	s_ashr_i32 s1, s0, 31
	s_ashr_i32 s19, s18, 31
	v_lshl_add_u64 v[4:5], v[40:41], 0, s[14:15]
	v_lshl_add_u64 v[6:7], v[42:43], 0, s[16:17]
	s_lshl_b64 s[16:17], s[0:1], 12
	v_lshl_add_u64 v[66:67], v[44:45], 0, s[14:15]
	s_lshl_b64 s[14:15], s[18:19], 12
	s_add_u32 s5, s2, s14
	s_addc_u32 s19, s3, s15
	s_add_u32 s14, s5, 0x2000
	global_load_dwordx4 v[32:35], v[48:49], off
	global_load_dwordx2 v[86:87], v[4:5], off
	global_load_dwordx2 v[84:85], v[4:5], off offset:512
	global_load_dwordx2 v[82:83], v[4:5], off offset:1024
	global_load_dwordx2 v[80:81], v[4:5], off offset:1536
	global_load_dwordx2 v[78:79], v[4:5], off offset:2048
	global_load_dwordx2 v[76:77], v[4:5], off offset:2560
	global_load_dwordx2 v[74:75], v[4:5], off offset:3072
	global_load_dwordx2 v[72:73], v[4:5], off offset:3584
	global_load_dwordx4 v[24:27], v[6:7], off nt
	global_load_dwordx4 v[16:19], v[6:7], off offset:1024 nt
	global_load_dwordx4 v[8:11], v[6:7], off offset:2048 nt
	global_load_dwordx4 v[0:3], v[6:7], off offset:3072 nt
	v_lshl_add_u64 v[36:37], v[42:43], 0, s[16:17]
	s_addc_u32 s15, s19, 0
	global_load_dwordx4 v[28:31], v[36:37], off nt
	global_load_dwordx4 v[20:23], v[36:37], off offset:1024 nt
	global_load_dwordx4 v[12:15], v[36:37], off offset:2048 nt
	global_load_dwordx4 v[4:7], v[36:37], off offset:3072 nt
	s_lshl_b64 s[0:1], s[0:1], 11
	global_load_dwordx4 v[36:39], v94, s[14:15]
	s_add_u32 s16, s5, 0x3000
	s_addc_u32 s17, s19, 0
	s_add_u32 s18, s5, 0x4000
	v_lshl_add_u64 v[68:69], v[44:45], 0, s[0:1]
	s_addc_u32 s19, s19, 0
	s_and_b32 s0, s21, 0x8000
	s_and_b32 s1, s9, 0xfffff000
	s_and_b32 s5, s4, 0xffe
	s_add_i32 s0, s0, s1
	s_or_b32 s0, s0, s5
	s_ashr_i32 s1, s0, 31
	s_lshl_b64 s[0:1], s[0:1], 11
	v_lshl_add_u64 v[70:71], v[46:47], 0, s[0:1]
	s_add_i32 s21, s21, s22
	s_add_i32 s4, s4, s23
	global_load_dwordx4 v[152:155], v95, s[14:15]
	global_load_dwordx4 v[156:159], v[50:51], off
	global_load_dwordx4 v[160:163], v96, s[14:15]
	global_load_dwordx4 v[164:167], v[52:53], off
	global_load_dwordx4 v[168:171], v97, s[14:15]
	global_load_dwordx4 v[172:175], v[54:55], off
	global_load_dwordx4 v[176:179], v94, s[18:19]
	global_load_dwordx4 v[180:183], v[56:57], off
	global_load_dwordx4 v[184:187], v94, s[16:17]
	global_load_dwordx4 v[188:191], v95, s[18:19]
	global_load_dwordx4 v[192:195], v[58:59], off
	global_load_dwordx4 v[196:199], v95, s[16:17]
	global_load_dwordx4 v[200:203], v96, s[18:19]
	global_load_dwordx4 v[204:207], v[60:61], off
	global_load_dwordx4 v[220:223], v96, s[16:17]
	global_load_dwordx4 v[224:227], v97, s[18:19]
	global_load_dwordx4 v[228:231], v[62:63], off
	global_load_dwordx4 v[232:235], v97, s[16:17]
	s_waitcnt vmcnt(34)
	v_lshlrev_b32_e32 v98, 16, v86
	v_and_b32_e32 v99, 0xffff0000, v86
	v_lshlrev_b32_e32 v86, 16, v87
	v_and_b32_e32 v87, 0xffff0000, v87
	s_waitcnt vmcnt(33)
	v_lshlrev_b32_e32 v101, 16, v85
	v_lshlrev_b32_e32 v100, 16, v84
	v_and_b32_e32 v85, 0xffff0000, v85
	v_and_b32_e32 v84, 0xffff0000, v84
	s_waitcnt vmcnt(30)
	v_lshlrev_b32_e32 v108, 16, v78
	v_and_b32_e32 v109, 0xffff0000, v78
	v_lshlrev_b32_e32 v78, 16, v79
	v_and_b32_e32 v79, 0xffff0000, v79
	s_waitcnt vmcnt(29)
	v_lshlrev_b32_e32 v111, 16, v77
	v_lshlrev_b32_e32 v110, 16, v76
	v_and_b32_e32 v77, 0xffff0000, v77
	v_and_b32_e32 v76, 0xffff0000, v76
	v_lshlrev_b32_e32 v102, 16, v82
	v_and_b32_e32 v103, 0xffff0000, v82
	v_lshlrev_b32_e32 v82, 16, v83
	v_and_b32_e32 v83, 0xffff0000, v83
	v_lshlrev_b32_e32 v105, 16, v80
	s_waitcnt vmcnt(27)
	v_lshlrev_b32_e32 v115, 16, v72
	v_mul_f32_e32 v104, v87, v87
	v_pk_mul_f32 v[118:119], v[84:85], v[84:85]
	v_mul_f32_e32 v114, v99, v99
	v_mul_f32_e32 v124, v79, v79
	v_pk_mul_f32 v[126:127], v[76:77], v[76:77]
	v_mul_f32_e32 v128, v109, v109
	v_and_b32_e32 v107, 0xffff0000, v80
	v_lshlrev_b32_e32 v112, 16, v74
	v_and_b32_e32 v113, 0xffff0000, v74
	v_lshlrev_b32_e32 v74, 16, v75
	v_and_b32_e32 v75, 0xffff0000, v75
	v_mov_b32_e32 v121, v105
	v_mul_f32_e32 v120, v103, v103
	v_mul_f32_e32 v122, v83, v83
	v_mov_b32_e32 v123, v115
	v_mov_b32_e32 v134, v100
	v_mov_b32_e32 v135, v84
	v_mov_b32_e32 v84, v101
	v_mov_b32_e32 v136, v110
	v_mov_b32_e32 v137, v76
	v_mov_b32_e32 v76, v111
	v_pk_fma_f32 v[140:141], v[86:87], v[86:87], v[104:105] op_sel_hi:[1,1,0]
	v_pk_fma_f32 v[100:101], v[100:101], v[100:101], v[118:119]
	v_pk_fma_f32 v[118:119], v[98:99], v[98:99], v[114:115] op_sel_hi:[1,1,0]
	v_pk_fma_f32 v[124:125], v[78:79], v[78:79], v[124:125] op_sel_hi:[1,1,0]
	v_pk_fma_f32 v[110:111], v[110:111], v[110:111], v[126:127]
	v_pk_fma_f32 v[126:127], v[108:109], v[108:109], v[128:129] op_sel_hi:[1,1,0]
	v_lshlrev_b32_e32 v80, 16, v81
	v_and_b32_e32 v81, 0xffff0000, v81
	v_and_b32_e32 v117, 0xffff0000, v72
	v_lshlrev_b32_e32 v72, 16, v73
	v_and_b32_e32 v73, 0xffff0000, v73
	v_mul_f32_e32 v133, v107, v107
	v_mul_f32_e32 v130, v113, v113
	v_mul_f32_e32 v132, v75, v75
	v_pk_fma_f32 v[142:143], v[102:103], v[102:103], v[120:121] op_sel_hi:[1,1,0]
	v_pk_fma_f32 v[144:145], v[82:83], v[82:83], v[122:123] op_sel_hi:[1,1,0]
	v_mov_b32_e32 v104, v118
	v_mov_b32_e32 v120, v140
	v_mov_b32_e32 v114, v126
	v_mov_b32_e32 v122, v124
	v_mul_f32_e32 v139, v80, v80
	v_mul_f32_e32 v146, v81, v81
	v_mul_f32_e32 v147, v117, v117
	v_mul_f32_e32 v148, v72, v72
	v_mul_f32_e32 v149, v73, v73
	v_mov_b32_e32 v106, v105
	v_mov_b32_e32 v116, v115
	v_pk_fma_f32 v[128:129], v[112:113], v[112:113], v[130:131] op_sel_hi:[1,1,0]
	v_pk_fma_f32 v[130:131], v[74:75], v[74:75], v[132:133] op_sel_hi:[1,1,0]
	v_pk_add_f32 v[118:119], v[118:119], v[140:141]
	v_pk_add_f32 v[100:101], v[100:101], v[100:101] op_sel:[0,1] op_sel_hi:[1,0]
	v_pk_add_f32 v[124:125], v[126:127], v[124:125]
	v_pk_add_f32 v[110:111], v[110:111], v[110:111] op_sel:[0,1] op_sel_hi:[1,0]
	v_pk_mul_f32 v[104:105], v[104:105], v[120:121]
	v_pk_mul_f32 v[114:115], v[114:115], v[122:123]
	v_mov_b32_e32 v143, v139
	v_mov_b32_e32 v145, v146
	v_mov_b32_e32 v129, v148
	v_mov_b32_e32 v131, v149
	v_mov_b32_e32 v101, v133
	v_mov_b32_e32 v111, v147
	v_mov_b32_e32 v119, v105
	v_mov_b32_e32 v125, v115
	v_pk_add_f32 v[120:121], v[142:143], v[144:145]
	v_pk_add_f32 v[122:123], v[128:129], v[130:131]
	s_waitcnt vmcnt(0)
	v_pk_mul_f32 v[34:35], v[38:39], v[34:35]
	v_pk_mul_f32 v[32:33], v[36:37], v[32:33]
	v_pk_add_f32 v[36:37], v[118:119], v[100:101]
	v_pk_add_f32 v[38:39], v[124:125], v[110:111]
	v_pk_add_f32 v[36:37], v[36:37], v[120:121]
	v_pk_add_f32 v[38:39], v[38:39], v[122:123]
	v_mov_b32_e32 v101, v36
	v_mov_b32_e32 v100, v38
	v_mov_b32_e32 v36, v39
	v_pk_add_f32 v[36:37], v[100:101], v[36:37]
	ds_bpermute_b32 v39, v88, v37
	ds_bpermute_b32 v38, v88, v36
	s_waitcnt lgkmcnt(0)
	v_pk_add_f32 v[36:37], v[36:37], v[38:39]
	ds_bpermute_b32 v39, v89, v37
	ds_bpermute_b32 v38, v89, v36
	s_waitcnt lgkmcnt(0)
	v_pk_add_f32 v[36:37], v[36:37], v[38:39]
	ds_bpermute_b32 v39, v90, v37
	ds_bpermute_b32 v38, v90, v36
	s_waitcnt lgkmcnt(0)
	v_pk_add_f32 v[36:37], v[36:37], v[38:39]
	ds_bpermute_b32 v39, v91, v37
	ds_bpermute_b32 v38, v91, v36
	s_waitcnt lgkmcnt(0)
	v_pk_add_f32 v[36:37], v[36:37], v[38:39]
	ds_bpermute_b32 v39, v92, v37
	ds_bpermute_b32 v38, v92, v36
	s_waitcnt lgkmcnt(0)
	v_pk_add_f32 v[36:37], v[36:37], v[38:39]
	ds_bpermute_b32 v39, v93, v37
	ds_bpermute_b32 v38, v93, v36
	s_waitcnt lgkmcnt(0)
	v_pk_add_f32 v[36:37], v[36:37], v[38:39]
	s_nop 0
	v_pk_fma_f32 v[36:37], v[36:37], s[8:9], v[64:65] op_sel_hi:[1,0,0]
	s_nop 0
	v_mul_f32_e32 v38, 0x4b800000, v37
	v_cmp_gt_f32_e64 s[0:1], s24, v37
	v_mul_f32_e32 v39, 0x4b800000, v36
	v_cmp_gt_f32_e32 vcc, s24, v36
	v_cndmask_b32_e64 v37, v37, v38, s[0:1]
	v_rsq_f32_e32 v37, v37
	v_cndmask_b32_e32 v36, v36, v39, vcc
	v_rsq_f32_e32 v36, v36
	v_mul_f32_e32 v38, 0x45800000, v37
	v_cndmask_b32_e64 v37, v37, v38, s[0:1]
	v_mul_f32_e32 v39, 0x45800000, v36
	v_cndmask_b32_e32 v38, v36, v39, vcc
	v_mul_f32_e32 v36, 0.5, v37
	v_mul_f32_e32 v38, 0.5, v38
	v_pk_mul_f32 v[98:99], v[36:37], v[98:99] op_sel_hi:[0,1]
	v_pk_mul_f32 v[86:87], v[36:37], v[86:87] op_sel_hi:[0,1]
	v_pk_mul_f32 v[100:101], v[38:39], v[108:109] op_sel_hi:[0,1]
	v_pk_mul_f32 v[78:79], v[38:39], v[78:79] op_sel_hi:[0,1]
	v_pk_mul_f32 v[104:105], v[36:37], v[134:135] op_sel_hi:[0,1]
	v_pk_mul_f32 v[84:85], v[36:37], v[84:85] op_sel_hi:[0,1]
	v_pk_mul_f32 v[108:109], v[38:39], v[136:137] op_sel_hi:[0,1]
	v_pk_mul_f32 v[76:77], v[38:39], v[76:77] op_sel_hi:[0,1]
	v_pk_mul_f32 v[102:103], v[36:37], v[102:103] op_sel_hi:[0,1]
	v_pk_mul_f32 v[82:83], v[36:37], v[82:83] op_sel_hi:[0,1]
	v_pk_mul_f32 v[110:111], v[38:39], v[112:113] op_sel_hi:[0,1]
	v_pk_mul_f32 v[74:75], v[38:39], v[74:75] op_sel_hi:[0,1]
	v_pk_mul_f32 v[106:107], v[36:37], v[106:107] op_sel_hi:[0,1]
	v_pk_mul_f32 v[36:37], v[36:37], v[80:81] op_sel_hi:[0,1]
	v_pk_mul_f32 v[80:81], v[38:39], v[116:117] op_sel_hi:[0,1]
	v_pk_mul_f32 v[38:39], v[38:39], v[72:73] op_sel_hi:[0,1]
	v_pk_fma_f32 v[72:73], v[34:35], v[86:87], v[26:27]
	v_pk_fma_f32 v[86:87], v[32:33], v[98:99], v[24:25]
	v_pk_fma_f32 v[34:35], v[34:35], v[78:79], v[30:31]
	v_pk_fma_f32 v[32:33], v[32:33], v[100:101], v[28:29]
	v_cvt_pk_bf16_f32 v24, v86, v87
	v_cvt_pk_bf16_f32 v25, v72, v73
	v_cvt_pk_bf16_f32 v26, v32, v33
	v_cvt_pk_bf16_f32 v27, v34, v35
	global_store_dwordx2 v[66:67], v[24:25], off
	global_store_dwordx2 v[68:69], v[26:27], off
	s_nop 0
	v_pk_mul_f32 v[78:79], v[72:73], v[72:73]
	v_pk_mul_f32 v[98:99], v[86:87], v[86:87]
	v_pk_mul_f32 v[100:101], v[34:35], v[34:35]
	v_pk_mul_f32 v[26:27], v[154:155], v[158:159]
	v_pk_mul_f32 v[24:25], v[152:153], v[156:157]
	v_pk_fma_f32 v[28:29], v[26:27], v[84:85], v[18:19]
	v_pk_fma_f32 v[30:31], v[24:25], v[104:105], v[16:17]
	v_pk_fma_f32 v[26:27], v[26:27], v[76:77], v[22:23]
	v_pk_fma_f32 v[24:25], v[24:25], v[108:109], v[20:21]
	v_cvt_pk_bf16_f32 v16, v30, v31
	v_cvt_pk_bf16_f32 v17, v28, v29
	v_cvt_pk_bf16_f32 v18, v24, v25
	v_cvt_pk_bf16_f32 v19, v26, v27
	global_store_dwordx2 v[66:67], v[16:17], off offset:512
	global_store_dwordx2 v[68:69], v[18:19], off offset:512
	s_nop 0
	v_pk_mul_f32 v[76:77], v[32:33], v[32:33]
	v_pk_mov_b32 v[84:85], v[98:99], v[78:79] op_sel:[1,0]
	v_mov_b32_e32 v99, v79
	v_pk_mov_b32 v[78:79], v[76:77], v[100:101] op_sel:[1,0]
	v_mov_b32_e32 v77, v101
	v_pk_add_f32 v[84:85], v[84:85], v[98:99]
	v_pk_add_f32 v[76:77], v[78:79], v[76:77]
	v_pk_add_f32 v[78:79], v[84:85], v[84:85] op_sel:[0,1] op_sel_hi:[1,0]
	v_pk_mul_f32 v[84:85], v[30:31], v[30:31]
	v_pk_mul_f32 v[98:99], v[26:27], v[26:27]
	v_pk_add_f32 v[76:77], v[76:77], v[76:77] op_sel:[0,1] op_sel_hi:[1,0]
	v_pk_mul_f32 v[18:19], v[162:163], v[166:167]
	v_pk_mul_f32 v[16:17], v[160:161], v[164:165]
	v_pk_fma_f32 v[20:21], v[82:83], v[18:19], v[10:11]
	v_pk_fma_f32 v[22:23], v[102:103], v[16:17], v[8:9]
	v_pk_fma_f32 v[18:19], v[18:19], v[74:75], v[14:15]
	v_pk_fma_f32 v[16:17], v[16:17], v[110:111], v[12:13]
	v_cvt_pk_bf16_f32 v8, v22, v23
	v_cvt_pk_bf16_f32 v9, v20, v21
	v_cvt_pk_bf16_f32 v10, v16, v17
	v_cvt_pk_bf16_f32 v11, v18, v19
	global_store_dwordx2 v[66:67], v[8:9], off offset:1024
	global_store_dwordx2 v[68:69], v[10:11], off offset:1024
	s_nop 0
	v_pk_mul_f32 v[74:75], v[28:29], v[28:29]
	v_pk_mul_f32 v[82:83], v[24:25], v[24:25]
	v_pk_mov_b32 v[100:101], v[84:85], v[74:75] op_sel:[1,0]
	v_mov_b32_e32 v85, v75
	v_pk_mov_b32 v[74:75], v[82:83], v[98:99] op_sel:[1,0]
	v_mov_b32_e32 v83, v99
	v_pk_add_f32 v[84:85], v[100:101], v[84:85]
	v_pk_add_f32 v[74:75], v[74:75], v[82:83]
	v_pk_add_f32 v[82:83], v[84:85], v[84:85] op_sel:[0,1] op_sel_hi:[1,0]
	v_mul_f32_e32 v84, v23, v23
	v_mul_f32_e32 v98, v21, v21
	v_mul_f32_e32 v100, v17, v17
	v_mul_f32_e32 v102, v19, v19
	v_pk_add_f32 v[74:75], v[74:75], v[74:75] op_sel:[0,1] op_sel_hi:[1,0]
	v_pk_fma_f32 v[84:85], v[22:23], v[22:23], v[84:85] op_sel_hi:[1,1,0]
	v_pk_fma_f32 v[98:99], v[20:21], v[20:21], v[98:99] op_sel_hi:[1,1,0]
	v_pk_fma_f32 v[100:101], v[16:17], v[16:17], v[100:101] op_sel_hi:[1,1,0]
	v_pk_fma_f32 v[102:103], v[18:19], v[18:19], v[102:103] op_sel_hi:[1,1,0]
	v_pk_mul_f32 v[10:11], v[170:171], v[174:175]
	v_pk_mul_f32 v[8:9], v[168:169], v[172:173]
	v_pk_fma_f32 v[12:13], v[36:37], v[10:11], v[2:3]
	v_pk_fma_f32 v[14:15], v[106:107], v[8:9], v[0:1]
	v_pk_fma_f32 v[36:37], v[38:39], v[10:11], v[6:7]
	v_pk_fma_f32 v[38:39], v[80:81], v[8:9], v[4:5]
	v_cvt_pk_bf16_f32 v0, v14, v15
	v_cvt_pk_bf16_f32 v1, v12, v13
	v_cvt_pk_bf16_f32 v2, v38, v39
	v_cvt_pk_bf16_f32 v3, v36, v37
	global_store_dwordx2 v[66:67], v[0:1], off offset:1536
	global_store_dwordx2 v[68:69], v[2:3], off offset:1536
	s_nop 0
	v_mul_f32_e32 v79, v14, v14
	v_mul_f32_e32 v83, v15, v15
	v_mul_f32_e32 v85, v12, v12
	v_mul_f32_e32 v99, v13, v13
	v_mul_f32_e32 v101, v38, v38
	v_mul_f32_e32 v103, v39, v39
	v_mul_f32_e32 v77, v36, v36
	v_mul_f32_e32 v75, v37, v37
	v_pk_add_f32 v[66:67], v[78:79], v[82:83]
	v_pk_add_f32 v[68:69], v[84:85], v[98:99]
	v_pk_add_f32 v[78:79], v[100:101], v[102:103]
	v_pk_add_f32 v[74:75], v[76:77], v[74:75]
	v_pk_add_f32 v[66:67], v[66:67], v[68:69]
	v_pk_add_f32 v[68:69], v[78:79], v[74:75]
	v_mov_b32_e32 v75, v66
	v_mov_b32_e32 v74, v68
	v_mov_b32_e32 v66, v69
	v_pk_add_f32 v[66:67], v[74:75], v[66:67]
	ds_bpermute_b32 v69, v88, v67
	ds_bpermute_b32 v68, v88, v66
	s_waitcnt lgkmcnt(0)
	v_pk_add_f32 v[66:67], v[66:67], v[68:69]
	ds_bpermute_b32 v69, v89, v67
	ds_bpermute_b32 v68, v89, v66
	s_waitcnt lgkmcnt(0)
	v_pk_add_f32 v[66:67], v[66:67], v[68:69]
	ds_bpermute_b32 v69, v90, v67
	ds_bpermute_b32 v68, v90, v66
	s_waitcnt lgkmcnt(0)
	v_pk_add_f32 v[66:67], v[66:67], v[68:69]
	ds_bpermute_b32 v69, v91, v67
	ds_bpermute_b32 v68, v91, v66
	s_waitcnt lgkmcnt(0)
	v_pk_add_f32 v[66:67], v[66:67], v[68:69]
	ds_bpermute_b32 v69, v92, v67
	ds_bpermute_b32 v68, v92, v66
	s_waitcnt lgkmcnt(0)
	v_pk_add_f32 v[66:67], v[66:67], v[68:69]
	ds_bpermute_b32 v69, v93, v67
	ds_bpermute_b32 v68, v93, v66
	s_waitcnt lgkmcnt(0)
	v_pk_add_f32 v[66:67], v[66:67], v[68:69]
	s_nop 0
	v_pk_fma_f32 v[66:67], v[66:67], s[8:9], v[64:65] op_sel_hi:[1,0,0]
	s_add_i32 s9, s9, s20
	v_mul_f32_e32 v68, 0x4b800000, v67
	v_cmp_gt_f32_e64 s[0:1], s24, v67
	v_mul_f32_e32 v69, 0x4b800000, v66
	v_cmp_gt_f32_e32 vcc, s24, v66
	v_cndmask_b32_e64 v67, v67, v68, s[0:1]
	v_rsq_f32_e32 v67, v67
	v_cndmask_b32_e32 v66, v66, v69, vcc
	v_rsq_f32_e32 v68, v66
	s_cmp_lt_i32 s9, 0x8000
	v_mul_f32_e32 v66, 0x45800000, v67
	v_cndmask_b32_e64 v66, v67, v66, s[0:1]
	v_mul_f32_e32 v69, 0x45800000, v68
	v_cndmask_b32_e32 v68, v68, v69, vcc
	v_pk_mul_f32 v[74:75], v[86:87], v[66:67] op_sel_hi:[1,0]
	v_pk_mul_f32 v[72:73], v[72:73], v[66:67] op_sel_hi:[1,0]
	v_pk_add_f32 v[2:3], v[178:179], 1.0 op_sel_hi:[1,0]
	v_pk_add_f32 v[0:1], v[176:177], 1.0 op_sel_hi:[1,0]
	v_pk_mul_f32 v[2:3], v[182:183], v[2:3]
	v_pk_mul_f32 v[0:1], v[180:181], v[0:1]
	v_pk_mul_f32 v[32:33], v[32:33], v[68:69] op_sel_hi:[1,0]
	v_pk_mul_f32 v[34:35], v[34:35], v[68:69] op_sel_hi:[1,0]
	v_pk_fma_f32 v[4:5], v[2:3], v[72:73], v[186:187]
	v_pk_fma_f32 v[6:7], v[0:1], v[74:75], v[184:185]
	v_pk_fma_f32 v[2:3], v[2:3], v[34:35], v[186:187]
	v_pk_fma_f32 v[0:1], v[0:1], v[32:33], v[184:185]
	v_cvt_pk_bf16_f32 v6, v6, v7
	v_cvt_pk_bf16_f32 v7, v4, v5
	v_cvt_pk_bf16_f32 v0, v0, v1
	v_cvt_pk_bf16_f32 v1, v2, v3
	global_store_dwordx2 v[70:71], v[6:7], off
	global_store_dwordx2 v[70:71], v[0:1], off offset:2048
	s_nop 0
	v_pk_mul_f32 v[30:31], v[30:31], v[66:67] op_sel_hi:[1,0]
	v_pk_mul_f32 v[28:29], v[28:29], v[66:67] op_sel_hi:[1,0]
	v_pk_mul_f32 v[24:25], v[24:25], v[68:69] op_sel_hi:[1,0]
	v_pk_mul_f32 v[26:27], v[26:27], v[68:69] op_sel_hi:[1,0]
	v_pk_mul_f32 v[22:23], v[22:23], v[66:67] op_sel_hi:[1,0]
	v_pk_mul_f32 v[20:21], v[20:21], v[66:67] op_sel_hi:[1,0]
	v_pk_mul_f32 v[16:17], v[16:17], v[68:69] op_sel_hi:[1,0]
	v_pk_mul_f32 v[18:19], v[18:19], v[68:69] op_sel_hi:[1,0]
	v_pk_mul_f32 v[14:15], v[14:15], v[66:67] op_sel_hi:[1,0]
	v_pk_mul_f32 v[12:13], v[12:13], v[66:67] op_sel_hi:[1,0]
	v_pk_add_f32 v[2:3], v[190:191], 1.0 op_sel_hi:[1,0]
	v_pk_add_f32 v[0:1], v[188:189], 1.0 op_sel_hi:[1,0]
	v_pk_mul_f32 v[2:3], v[194:195], v[2:3]
	v_pk_mul_f32 v[0:1], v[192:193], v[0:1]
	v_pk_fma_f32 v[4:5], v[2:3], v[28:29], v[198:199]
	v_pk_fma_f32 v[6:7], v[0:1], v[30:31], v[196:197]
	v_pk_fma_f32 v[2:3], v[2:3], v[26:27], v[198:199]
	v_pk_fma_f32 v[0:1], v[0:1], v[24:25], v[196:197]
	v_cvt_pk_bf16_f32 v6, v6, v7
	v_cvt_pk_bf16_f32 v7, v4, v5
	v_cvt_pk_bf16_f32 v0, v0, v1
	v_cvt_pk_bf16_f32 v1, v2, v3
	global_store_dwordx2 v[70:71], v[6:7], off offset:512
	global_store_dwordx2 v[70:71], v[0:1], off offset:2560
	s_nop 0
	v_pk_add_f32 v[2:3], v[202:203], 1.0 op_sel_hi:[1,0]
	v_pk_add_f32 v[0:1], v[200:201], 1.0 op_sel_hi:[1,0]
	v_pk_mul_f32 v[2:3], v[206:207], v[2:3]
	v_pk_mul_f32 v[0:1], v[204:205], v[0:1]
	v_pk_fma_f32 v[4:5], v[20:21], v[2:3], v[222:223]
	v_pk_fma_f32 v[6:7], v[22:23], v[0:1], v[220:221]
	v_pk_fma_f32 v[2:3], v[18:19], v[2:3], v[222:223]
	v_pk_fma_f32 v[0:1], v[16:17], v[0:1], v[220:221]
	v_cvt_pk_bf16_f32 v6, v6, v7
	v_cvt_pk_bf16_f32 v7, v4, v5
	v_cvt_pk_bf16_f32 v0, v0, v1
	v_cvt_pk_bf16_f32 v1, v2, v3
	global_store_dwordx2 v[70:71], v[6:7], off offset:1024
	global_store_dwordx2 v[70:71], v[0:1], off offset:3072
	s_nop 0
	v_pk_mul_f32 v[16:17], v[38:39], v[68:69] op_sel_hi:[1,0]
	v_pk_mul_f32 v[18:19], v[36:37], v[68:69] op_sel_hi:[1,0]
	v_pk_add_f32 v[2:3], v[226:227], 1.0 op_sel_hi:[1,0]
	v_pk_add_f32 v[0:1], v[224:225], 1.0 op_sel_hi:[1,0]
	v_pk_mul_f32 v[2:3], v[230:231], v[2:3]
	v_pk_mul_f32 v[0:1], v[228:229], v[0:1]
	v_pk_fma_f32 v[4:5], v[12:13], v[2:3], v[234:235]
	v_pk_fma_f32 v[6:7], v[14:15], v[0:1], v[232:233]
	v_pk_fma_f32 v[2:3], v[18:19], v[2:3], v[234:235]
	v_pk_fma_f32 v[0:1], v[16:17], v[0:1], v[232:233]
	v_cvt_pk_bf16_f32 v6, v6, v7
	v_cvt_pk_bf16_f32 v7, v4, v5
	v_cvt_pk_bf16_f32 v0, v0, v1
	v_cvt_pk_bf16_f32 v1, v2, v3
	global_store_dwordx2 v[70:71], v[6:7], off offset:1536
	global_store_dwordx2 v[70:71], v[0:1], off offset:3584
	s_cbranch_scc1 .LBB0_316

.LBB0_1103:
	s_ashr_i32 s7, s6, 31
	s_add_i32 s0, s6, 1
	s_ashr_i32 s16, s9, 11
	s_add_i32 s2, s6, 2
	s_add_i32 s4, s6, 3
	s_lshl_b64 s[10:11], s[6:7], 11
	s_ashr_i32 s1, s0, 31
	s_mul_i32 s16, s16, 9
	s_ashr_i32 s3, s2, 31
	s_ashr_i32 s5, s4, 31
	v_lshl_add_u64 v[22:23], v[4:5], 0, s[10:11]
	v_lshl_add_u64 v[24:25], v[6:7], 0, s[10:11]
	s_lshl_b64 s[10:11], s[0:1], 11
	s_ashr_i32 s17, s16, 31
	global_load_dwordx4 v[0:3], v[10:11], off
	s_lshl_b64 s[18:19], s[2:3], 11
	s_lshl_b64 s[20:21], s[4:5], 11
	global_load_dwordx2 v[36:37], v[24:25], off
	global_load_dwordx2 v[38:39], v[22:23], off
	global_load_dwordx2 v[40:41], v[22:23], off offset:512
	global_load_dwordx2 v[42:43], v[22:23], off offset:1024
	global_load_dwordx2 v[44:45], v[22:23], off offset:1536
	global_load_dwordx2 v[46:47], v[22:23], off offset:2048
	global_load_dwordx2 v[50:51], v[22:23], off offset:2560
	global_load_dwordx2 v[76:77], v[24:25], off offset:512
	global_load_dwordx2 v[48:49], v[24:25], off offset:1024
	global_load_dwordx2 v[20:21], v[24:25], off offset:1536
	v_lshl_add_u64 v[26:27], v[6:7], 0, s[10:11]
	global_load_dwordx2 v[52:53], v[22:23], off offset:3072
	global_load_dwordx2 v[54:55], v[22:23], off offset:3584
	s_lshl_b64 s[10:11], s[16:17], 12
	s_add_u32 s10, s88, s10
	v_add_co_u32_e32 v30, vcc, s14, v22
	s_addc_u32 s11, s89, s11
	v_lshl_add_u64 v[28:29], v[6:7], 0, s[18:19]
	v_addc_co_u32_e32 v31, vcc, 0, v23, vcc
	v_lshl_add_u64 v[32:33], v[6:7], 0, s[20:21]
	global_load_dwordx2 v[60:61], v[26:27], off
	global_load_dwordx2 v[62:63], v[28:29], off
	global_load_dwordx2 v[66:67], v[32:33], off
	global_load_dwordx2 v[78:79], v[26:27], off offset:512
	global_load_dwordx2 v[56:57], v[26:27], off offset:1024
	global_load_dwordx2 v[22:23], v[26:27], off offset:1536
	global_load_dwordx2 v[84:85], v[30:31], off
	global_load_dwordx2 v[86:87], v[30:31], off offset:512
	global_load_dwordx2 v[88:89], v[30:31], off offset:1024
	global_load_dwordx2 v[90:91], v[30:31], off offset:1536
	global_load_dwordx2 v[80:81], v[28:29], off offset:512
	global_load_dwordx2 v[58:59], v[28:29], off offset:1024
	global_load_dwordx2 v[24:25], v[28:29], off offset:1536
	global_load_dwordx2 v[104:105], v[30:31], off offset:2048
	global_load_dwordx2 v[106:107], v[30:31], off offset:2560
	global_load_dwordx2 v[130:131], v[30:31], off offset:3072
	global_load_dwordx2 v[132:133], v[30:31], off offset:3584
	global_load_dwordx2 v[82:83], v[32:33], off offset:512
	global_load_dwordx2 v[64:65], v[32:33], off offset:1024
	global_load_dwordx2 v[26:27], v[32:33], off offset:1536
	s_add_u32 s10, s10, 0x8000
	s_addc_u32 s11, s11, 0
	global_load_dwordx4 v[126:129], v122, s[10:11]
	s_lshl_b64 s[0:1], s[0:1], 12
	s_lshl_b64 s[4:5], s[4:5], 12
	v_lshl_add_u64 v[30:31], v[8:9], 0, s[0:1]
	s_lshl_b64 s[2:3], s[2:3], 12
	v_lshl_add_u64 v[34:35], v[8:9], 0, s[4:5]
	v_lshl_add_u64 v[32:33], v[8:9], 0, s[2:3]
	s_lshl_b64 s[16:17], s[6:7], 12
	v_lshl_add_u64 v[28:29], v[8:9], 0, s[16:17]
	s_add_i32 s6, s6, s13
	global_load_dwordx4 v[220:223], v123, s[10:11]
	global_load_dwordx4 v[224:227], v[12:13], off
	global_load_dwordx4 v[228:231], v124, s[10:11]
	global_load_dwordx4 v[232:235], v[14:15], off
	global_load_dwordx4 v[236:239], v125, s[10:11]
	global_load_dwordx4 v[240:243], v[16:17], off
	s_waitcnt vmcnt(26)
	v_lshlrev_b32_e32 v138, 16, v60
	v_and_b32_e32 v113, 0xffff0000, v38
	v_and_b32_e32 v115, 0xffff0000, v39
	v_and_b32_e32 v97, 0xffff0000, v41
	v_and_b32_e32 v96, 0xffff0000, v40
	v_and_b32_e32 v69, 0xffff0000, v42
	v_and_b32_e32 v135, 0xffff0000, v46
	v_and_b32_e32 v137, 0xffff0000, v47
	v_lshlrev_b32_e32 v108, 16, v36
	v_and_b32_e32 v109, 0xffff0000, v36
	v_and_b32_e32 v71, 0xffff0000, v52
	v_and_b32_e32 v75, 0xffff0000, v53
	v_lshlrev_b32_e32 v110, 16, v37
	v_and_b32_e32 v111, 0xffff0000, v37
	v_lshlrev_b32_e32 v112, 16, v38
	v_lshlrev_b32_e32 v114, 16, v39
	v_lshlrev_b32_e32 v93, 16, v41
	v_lshlrev_b32_e32 v92, 16, v40
	v_lshlrev_b32_e32 v68, 16, v42
	v_lshlrev_b32_e32 v72, 16, v43
	v_and_b32_e32 v73, 0xffff0000, v43
	v_lshlrev_b32_e32 v41, 16, v44
	v_and_b32_e32 v37, 0xffff0000, v44
	v_lshlrev_b32_e32 v38, 16, v45
	v_and_b32_e32 v39, 0xffff0000, v45
	v_lshlrev_b32_e32 v134, 16, v46
	v_lshlrev_b32_e32 v136, 16, v47
	v_lshlrev_b32_e32 v95, 16, v51
	v_lshlrev_b32_e32 v94, 16, v50
	v_and_b32_e32 v99, 0xffff0000, v51
	v_and_b32_e32 v98, 0xffff0000, v50
	v_lshlrev_b32_e32 v70, 16, v52
	v_lshlrev_b32_e32 v74, 16, v53
	v_lshlrev_b32_e32 v47, 16, v54
	v_and_b32_e32 v43, 0xffff0000, v54
	v_lshlrev_b32_e32 v44, 16, v55
	v_and_b32_e32 v45, 0xffff0000, v55
	v_and_b32_e32 v139, 0xffff0000, v60
	v_lshlrev_b32_e32 v140, 16, v61
	v_and_b32_e32 v141, 0xffff0000, v61
	s_waitcnt vmcnt(24)
	v_lshlrev_b32_e32 v146, 16, v66
	v_and_b32_e32 v147, 0xffff0000, v66
	v_lshlrev_b32_e32 v148, 16, v67
	v_and_b32_e32 v149, 0xffff0000, v67
	v_mul_f32_e32 v36, v115, v115
	v_pk_mul_f32 v[150:151], v[96:97], v[96:97]
	v_mul_f32_e32 v40, v113, v113
	v_mul_f32_e32 v42, v69, v69
	v_mul_f32_e32 v50, v137, v137
	v_mul_f32_e32 v54, v135, v135
	v_mul_f32_e32 v60, v71, v71
	v_mul_f32_e32 v66, v75, v75
	s_waitcnt vmcnt(20)
	v_and_b32_e32 v159, 0xffff0000, v84
	v_and_b32_e32 v161, 0xffff0000, v85
	s_waitcnt vmcnt(19)
	v_and_b32_e32 v103, 0xffff0000, v87
	v_and_b32_e32 v102, 0xffff0000, v86
	s_waitcnt vmcnt(17)
	v_lshlrev_b32_e32 v55, 16, v90
	v_and_b32_e32 v51, 0xffff0000, v90
	s_waitcnt vmcnt(13)
	v_and_b32_e32 v163, 0xffff0000, v104
	v_and_b32_e32 v165, 0xffff0000, v105
	s_waitcnt vmcnt(10)
	v_lshlrev_b32_e32 v67, 16, v132
	v_and_b32_e32 v61, 0xffff0000, v132
	v_lshlrev_b32_e32 v142, 16, v62
	v_and_b32_e32 v143, 0xffff0000, v62
	v_lshlrev_b32_e32 v144, 16, v63
	v_and_b32_e32 v145, 0xffff0000, v63
	v_mul_f32_e32 v156, v38, v38
	v_mul_f32_e32 v46, v73, v73
	v_pk_mul_f32 v[154:155], v[98:99], v[98:99]
	v_lshlrev_b32_e32 v158, 16, v84
	v_lshlrev_b32_e32 v160, 16, v85
	v_lshlrev_b32_e32 v101, 16, v87
	v_lshlrev_b32_e32 v100, 16, v86
	v_lshlrev_b32_e32 v84, 16, v88
	v_and_b32_e32 v85, 0xffff0000, v88
	v_lshlrev_b32_e32 v88, 16, v89
	v_and_b32_e32 v89, 0xffff0000, v89
	v_lshlrev_b32_e32 v52, 16, v91
	v_and_b32_e32 v53, 0xffff0000, v91
	v_lshlrev_b32_e32 v162, 16, v104
	v_lshlrev_b32_e32 v164, 16, v105
	v_lshlrev_b32_e32 v105, 16, v107
	v_lshlrev_b32_e32 v104, 16, v106
	v_and_b32_e32 v107, 0xffff0000, v107
	v_and_b32_e32 v106, 0xffff0000, v106
	v_lshlrev_b32_e32 v86, 16, v130
	v_and_b32_e32 v87, 0xffff0000, v130
	v_lshlrev_b32_e32 v90, 16, v131
	v_and_b32_e32 v91, 0xffff0000, v131
	v_lshlrev_b32_e32 v62, 16, v133
	v_and_b32_e32 v63, 0xffff0000, v133
	v_pk_fma_f32 v[130:131], v[114:115], v[114:115], v[36:37] op_sel_hi:[1,1,0]
	v_pk_fma_f32 v[132:133], v[92:93], v[92:93], v[150:151]
	v_pk_fma_f32 v[150:151], v[112:113], v[112:113], v[40:41] op_sel_hi:[1,1,0]
	v_pk_fma_f32 v[166:167], v[68:69], v[68:69], v[42:43] op_sel_hi:[1,1,0]
	v_pk_fma_f32 v[170:171], v[136:137], v[136:137], v[50:51] op_sel_hi:[1,1,0]
	v_pk_fma_f32 v[172:173], v[134:135], v[134:135], v[54:55] op_sel_hi:[1,1,0]
	v_pk_fma_f32 v[174:175], v[70:71], v[70:71], v[60:61] op_sel_hi:[1,1,0]
	v_pk_fma_f32 v[176:177], v[74:75], v[74:75], v[66:67] op_sel_hi:[1,1,0]
	v_mul_f32_e32 v36, v161, v161
	v_pk_mul_f32 v[178:179], v[102:103], v[102:103]
	v_mul_f32_e32 v42, v159, v159
	v_mul_f32_e32 v60, v165, v165
	v_mul_f32_e32 v66, v163, v163
	v_mul_f32_e32 v186, v39, v39
	v_mov_b32_e32 v153, v41
	v_mul_f32_e32 v187, v44, v44
	v_mul_f32_e32 v188, v45, v45
	v_mov_b32_e32 v157, v47
	v_pk_fma_f32 v[168:169], v[72:73], v[72:73], v[46:47] op_sel_hi:[1,1,0]
	v_pk_fma_f32 v[154:155], v[94:95], v[94:95], v[154:155]
	v_mov_b32_e32 v181, v55
	v_mul_f32_e32 v54, v89, v89
	v_pk_mul_f32 v[182:183], v[106:107], v[106:107]
	v_mov_b32_e32 v185, v67
	v_mul_f32_e32 v180, v87, v87
	v_mul_f32_e32 v184, v91, v91
	v_mov_b32_e32 v40, v150
	v_mov_b32_e32 v152, v130
	v_pk_add_f32 v[130:131], v[150:151], v[130:131]
	v_mov_b32_e32 v167, v156
	v_mov_b32_e32 v46, v172
	v_mov_b32_e32 v156, v170
	v_pk_add_f32 v[150:151], v[172:173], v[170:171]
	v_pk_fma_f32 v[170:171], v[160:161], v[160:161], v[36:37] op_sel_hi:[1,1,0]
	v_pk_fma_f32 v[172:173], v[100:101], v[100:101], v[178:179]
	v_pk_fma_f32 v[178:179], v[158:159], v[158:159], v[42:43] op_sel_hi:[1,1,0]
	v_pk_fma_f32 v[190:191], v[164:165], v[164:165], v[60:61] op_sel_hi:[1,1,0]
	v_pk_fma_f32 v[192:193], v[162:163], v[162:163], v[66:67] op_sel_hi:[1,1,0]
	v_mul_f32_e32 v198, v37, v37
	v_mul_f32_e32 v199, v43, v43
	v_mul_f32_e32 v50, v85, v85
	v_pk_add_f32 v[132:133], v[132:133], v[132:133] op_sel:[0,1] op_sel_hi:[1,0]
	v_mov_b32_e32 v169, v186
	v_pk_add_f32 v[154:155], v[154:155], v[154:155] op_sel:[0,1] op_sel_hi:[1,0]
	v_mov_b32_e32 v175, v187
	v_mov_b32_e32 v177, v188
	v_pk_fma_f32 v[188:189], v[88:89], v[88:89], v[54:55] op_sel_hi:[1,1,0]
	v_pk_fma_f32 v[182:183], v[104:105], v[104:105], v[182:183]
	v_pk_fma_f32 v[194:195], v[86:87], v[86:87], v[180:181] op_sel_hi:[1,1,0]
	v_pk_fma_f32 v[196:197], v[90:91], v[90:91], v[184:185] op_sel_hi:[1,1,0]
	v_pk_mul_f32 v[152:153], v[40:41], v[152:153]
	v_pk_mul_f32 v[156:157], v[46:47], v[156:157]
	v_mov_b32_e32 v54, v178
	v_mov_b32_e32 v180, v170
	v_mov_b32_e32 v66, v192
	v_mov_b32_e32 v184, v190
	v_mul_f32_e32 v200, v51, v51
	v_mul_f32_e32 v201, v52, v52
	v_mul_f32_e32 v202, v53, v53
	v_mul_f32_e32 v203, v61, v61
	v_mul_f32_e32 v204, v62, v62
	v_mul_f32_e32 v205, v63, v63
	v_pk_fma_f32 v[186:187], v[84:85], v[84:85], v[50:51] op_sel_hi:[1,1,0]
	v_mov_b32_e32 v133, v198
	v_pk_add_f32 v[166:167], v[166:167], v[168:169]
	v_mov_b32_e32 v155, v199
	v_pk_add_f32 v[168:169], v[174:175], v[176:177]
	v_pk_add_f32 v[170:171], v[178:179], v[170:171]
	v_pk_add_f32 v[172:173], v[172:173], v[172:173] op_sel:[0,1] op_sel_hi:[1,0]
	v_pk_add_f32 v[174:175], v[192:193], v[190:191]
	v_pk_add_f32 v[176:177], v[182:183], v[182:183] op_sel:[0,1] op_sel_hi:[1,0]
	v_mov_b32_e32 v131, v153
	v_mov_b32_e32 v151, v157
	v_pk_mul_f32 v[152:153], v[54:55], v[180:181]
	v_pk_mul_f32 v[178:179], v[66:67], v[184:185]
	v_mov_b32_e32 v187, v201
	v_mov_b32_e32 v189, v202
	v_mov_b32_e32 v195, v204
	v_mov_b32_e32 v197, v205
	v_mov_b32_e32 v173, v200
	v_mov_b32_e32 v177, v203
	s_waitcnt vmcnt(0)
	v_pk_mul_f32 v[128:129], v[128:129], v[2:3]
	v_pk_mul_f32 v[126:127], v[126:127], v[0:1]
	v_pk_add_f32 v[0:1], v[130:131], v[132:133]
	v_pk_add_f32 v[2:3], v[150:151], v[154:155]
	v_mov_b32_e32 v171, v153
	v_mov_b32_e32 v175, v179
	v_pk_add_f32 v[156:157], v[186:187], v[188:189]
	v_pk_add_f32 v[180:181], v[194:195], v[196:197]
	v_pk_add_f32 v[0:1], v[0:1], v[166:167]
	v_pk_add_f32 v[2:3], v[2:3], v[168:169]
	v_pk_add_f32 v[130:131], v[170:171], v[172:173]
	v_pk_add_f32 v[132:133], v[174:175], v[176:177]
	v_mov_b32_e32 v150, v2
	v_mov_b32_e32 v151, v0
	v_mov_b32_e32 v0, v3
	v_pk_add_f32 v[2:3], v[130:131], v[156:157]
	v_pk_add_f32 v[130:131], v[132:133], v[180:181]
	v_pk_add_f32 v[0:1], v[150:151], v[0:1]
	v_mov_b32_e32 v132, v130
	v_mov_b32_e32 v133, v2
	v_mov_b32_e32 v2, v131
	ds_bpermute_b32 v131, v116, v1
	ds_bpermute_b32 v130, v116, v0
	v_pk_add_f32 v[2:3], v[132:133], v[2:3]
	ds_bpermute_b32 v133, v116, v3
	ds_bpermute_b32 v132, v116, v2
	v_mov_b32_e32 v50, v55
	s_waitcnt lgkmcnt(2)
	v_pk_add_f32 v[0:1], v[0:1], v[130:131]
	ds_bpermute_b32 v131, v117, v1
	ds_bpermute_b32 v130, v117, v0
	s_waitcnt lgkmcnt(2)
	v_pk_add_f32 v[2:3], v[2:3], v[132:133]
	ds_bpermute_b32 v133, v117, v3
	ds_bpermute_b32 v132, v117, v2
	v_mov_b32_e32 v60, v67
	s_waitcnt lgkmcnt(2)
	v_pk_add_f32 v[0:1], v[0:1], v[130:131]
	ds_bpermute_b32 v131, v118, v1
	ds_bpermute_b32 v130, v118, v0
	s_waitcnt lgkmcnt(2)
	v_pk_add_f32 v[2:3], v[2:3], v[132:133]
	ds_bpermute_b32 v133, v118, v3
	ds_bpermute_b32 v132, v118, v2
	s_waitcnt lgkmcnt(2)
	v_pk_add_f32 v[0:1], v[0:1], v[130:131]
	ds_bpermute_b32 v131, v119, v1
	ds_bpermute_b32 v130, v119, v0
	s_waitcnt lgkmcnt(2)
	v_pk_add_f32 v[2:3], v[2:3], v[132:133]
	ds_bpermute_b32 v133, v119, v3
	ds_bpermute_b32 v132, v119, v2
	s_waitcnt lgkmcnt(2)
	v_pk_add_f32 v[0:1], v[0:1], v[130:131]
	ds_bpermute_b32 v131, v120, v1
	ds_bpermute_b32 v130, v120, v0
	s_waitcnt lgkmcnt(2)
	v_pk_add_f32 v[2:3], v[2:3], v[132:133]
	ds_bpermute_b32 v133, v120, v3
	ds_bpermute_b32 v132, v120, v2
	s_waitcnt lgkmcnt(2)
	v_pk_add_f32 v[0:1], v[0:1], v[130:131]
	ds_bpermute_b32 v131, v121, v1
	ds_bpermute_b32 v130, v121, v0
	s_waitcnt lgkmcnt(2)
	v_pk_add_f32 v[2:3], v[2:3], v[132:133]
	ds_bpermute_b32 v133, v121, v3
	ds_bpermute_b32 v132, v121, v2
	s_waitcnt lgkmcnt(2)
	v_pk_add_f32 v[0:1], v[0:1], v[130:131]
	s_nop 0
	v_pk_fma_f32 v[0:1], v[0:1], s[8:9], v[18:19] op_sel_hi:[1,0,0]
	s_waitcnt lgkmcnt(0)
	v_pk_add_f32 v[2:3], v[2:3], v[132:133]
	v_mul_f32_e32 v36, 0x4b800000, v1
	v_mul_f32_e32 v40, 0x4b800000, v0
	v_cmp_gt_f32_e32 vcc, s15, v0
	v_pk_fma_f32 v[2:3], v[2:3], s[8:9], v[18:19] op_sel_hi:[1,0,0]
	v_cmp_gt_f32_e64 s[0:1], s15, v1
	v_cndmask_b32_e32 v0, v0, v40, vcc
	v_cmp_gt_f32_e64 s[4:5], s15, v3
	v_cndmask_b32_e64 v1, v1, v36, s[0:1]
	v_mul_f32_e32 v36, 0x4b800000, v3
	v_mul_f32_e32 v40, 0x4b800000, v2
	v_cmp_gt_f32_e64 s[2:3], s15, v2
	v_rsq_f32_e32 v1, v1
	v_rsq_f32_e32 v0, v0
	v_cndmask_b32_e64 v3, v3, v36, s[4:5]
	v_cndmask_b32_e64 v2, v2, v40, s[2:3]
	v_rsq_f32_e32 v3, v3
	v_rsq_f32_e32 v2, v2
	v_mul_f32_e32 v36, 0x45800000, v1
	v_mul_f32_e32 v40, 0x45800000, v0
	v_cndmask_b32_e64 v1, v1, v36, s[0:1]
	v_cndmask_b32_e32 v0, v0, v40, vcc
	v_mul_f32_e32 v36, 0x45800000, v3
	v_mul_f32_e32 v42, 0x45800000, v2
	v_mul_f32_e32 v40, 0.5, v1
	v_mul_f32_e32 v0, 0.5, v0
	v_cndmask_b32_e64 v1, v3, v36, s[4:5]
	v_cndmask_b32_e64 v2, v2, v42, s[2:3]
	v_mul_f32_e32 v46, 0.5, v1
	v_pk_mul_f32 v[112:113], v[40:41], v[112:113] op_sel_hi:[0,1]
	v_pk_mul_f32 v[114:115], v[40:41], v[114:115] op_sel_hi:[0,1]
	v_pk_mul_f32 v[130:131], v[0:1], v[134:135] op_sel_hi:[0,1]
	v_pk_mul_f32 v[132:133], v[0:1], v[136:137] op_sel_hi:[0,1]
	v_mul_f32_e32 v2, 0.5, v2
	v_pk_fma_f32 v[110:111], v[114:115], v[128:129], v[110:111]
	v_pk_fma_f32 v[108:109], v[112:113], v[126:127], v[108:109]
	v_pk_fma_f32 v[114:115], v[132:133], v[128:129], v[140:141]
	v_pk_fma_f32 v[112:113], v[130:131], v[126:127], v[138:139]
	v_pk_mul_f32 v[130:131], v[46:47], v[158:159] op_sel_hi:[0,1]
	v_pk_mul_f32 v[132:133], v[46:47], v[160:161] op_sel_hi:[0,1]
	v_pk_mul_f32 v[134:135], v[2:3], v[162:163] op_sel_hi:[0,1]
	v_pk_mul_f32 v[136:137], v[2:3], v[164:165] op_sel_hi:[0,1]
	global_store_dwordx4 v[28:29], v[108:111], off nt
	global_store_dwordx4 v[30:31], v[112:115], off nt
	v_lshlrev_b32_e32 v138, 16, v82
	v_pk_fma_f32 v[110:111], v[128:129], v[132:133], v[144:145]
	v_pk_fma_f32 v[108:109], v[126:127], v[130:131], v[142:143]
	v_pk_fma_f32 v[114:115], v[128:129], v[136:137], v[148:149]
	v_pk_fma_f32 v[112:113], v[126:127], v[134:135], v[146:147]
	global_store_dwordx4 v[32:33], v[108:111], off nt
	global_store_dwordx4 v[34:35], v[112:115], off nt
	s_nop 0
	v_lshlrev_b32_e32 v126, 16, v76
	v_and_b32_e32 v127, 0xffff0000, v76
	v_lshlrev_b32_e32 v128, 16, v77
	v_and_b32_e32 v129, 0xffff0000, v77
	v_mov_b32_e32 v76, v93
	v_mov_b32_e32 v77, v97
	v_mov_b32_e32 v93, v96
	v_lshlrev_b32_e32 v130, 16, v78
	v_and_b32_e32 v131, 0xffff0000, v78
	v_lshlrev_b32_e32 v132, 16, v79
	v_and_b32_e32 v133, 0xffff0000, v79
	v_lshlrev_b32_e32 v134, 16, v80
	v_and_b32_e32 v135, 0xffff0000, v80
	v_lshlrev_b32_e32 v136, 16, v81
	v_and_b32_e32 v137, 0xffff0000, v81
	v_and_b32_e32 v139, 0xffff0000, v82
	v_lshlrev_b32_e32 v140, 16, v83
	v_and_b32_e32 v141, 0xffff0000, v83
	v_mov_b32_e32 v78, v95
	v_mov_b32_e32 v79, v99
	v_mov_b32_e32 v95, v98
	v_mov_b32_e32 v80, v101
	v_mov_b32_e32 v81, v103
	v_mov_b32_e32 v82, v105
	v_mov_b32_e32 v83, v107
	v_mov_b32_e32 v101, v102
	v_mov_b32_e32 v105, v106
	v_pk_mul_f32 v[96:97], v[40:41], v[76:77] op_sel_hi:[0,1]
	v_pk_mul_f32 v[76:77], v[40:41], v[92:93] op_sel_hi:[0,1]
	v_pk_mul_f32 v[92:93], v[0:1], v[78:79] op_sel_hi:[0,1]
	v_pk_mul_f32 v[94:95], v[0:1], v[94:95] op_sel_hi:[0,1]
	v_pk_mul_f32 v[98:99], v[46:47], v[80:81] op_sel_hi:[0,1]
	v_pk_mul_f32 v[100:101], v[46:47], v[100:101] op_sel_hi:[0,1]
	v_pk_mul_f32 v[102:103], v[2:3], v[82:83] op_sel_hi:[0,1]
	v_pk_mul_f32 v[104:105], v[2:3], v[104:105] op_sel_hi:[0,1]
	v_pk_mul_f32 v[84:85], v[46:47], v[84:85] op_sel_hi:[0,1]
	v_pk_mul_f32 v[86:87], v[2:3], v[86:87] op_sel_hi:[0,1]
	v_mov_b32_e32 v36, v41
	v_mov_b32_e32 v42, v47
	s_add_i32 s9, s9, s12
	s_cmpk_lt_i32 s9, 0x4000
	v_pk_mul_f32 v[106:107], v[222:223], v[226:227]
	v_pk_mul_f32 v[108:109], v[220:221], v[224:225]
	v_pk_fma_f32 v[78:79], v[96:97], v[106:107], v[128:129]
	v_pk_fma_f32 v[76:77], v[76:77], v[108:109], v[126:127]
	v_pk_fma_f32 v[80:81], v[94:95], v[108:109], v[130:131]
	v_pk_fma_f32 v[82:83], v[92:93], v[106:107], v[132:133]
	v_pk_fma_f32 v[92:93], v[100:101], v[108:109], v[134:135]
	v_pk_fma_f32 v[94:95], v[98:99], v[106:107], v[136:137]
	v_pk_fma_f32 v[96:97], v[108:109], v[104:105], v[138:139]
	v_pk_fma_f32 v[98:99], v[106:107], v[102:103], v[140:141]
	global_store_dwordx4 v[28:29], v[76:79], off offset:1024 nt
	global_store_dwordx4 v[30:31], v[80:83], off offset:1024 nt
	global_store_dwordx4 v[32:33], v[92:95], off offset:1024 nt
	global_store_dwordx4 v[34:35], v[96:99], off offset:1024 nt
	s_nop 0
	v_lshlrev_b32_e32 v92, 16, v48
	v_and_b32_e32 v93, 0xffff0000, v48
	v_lshlrev_b32_e32 v48, 16, v49
	v_and_b32_e32 v49, 0xffff0000, v49
	v_lshlrev_b32_e32 v94, 16, v56
	v_and_b32_e32 v95, 0xffff0000, v56
	v_lshlrev_b32_e32 v96, 16, v57
	v_and_b32_e32 v97, 0xffff0000, v57
	v_lshlrev_b32_e32 v98, 16, v58
	v_and_b32_e32 v99, 0xffff0000, v58
	v_lshlrev_b32_e32 v100, 16, v59
	v_and_b32_e32 v101, 0xffff0000, v59
	v_pk_mul_f32 v[58:59], v[40:41], v[72:73] op_sel_hi:[0,1]
	v_pk_mul_f32 v[56:57], v[40:41], v[68:69] op_sel_hi:[0,1]
	v_lshlrev_b32_e32 v102, 16, v64
	v_and_b32_e32 v103, 0xffff0000, v64
	v_lshlrev_b32_e32 v64, 16, v65
	v_and_b32_e32 v65, 0xffff0000, v65
	v_pk_mul_f32 v[72:73], v[0:1], v[74:75] op_sel_hi:[0,1]
	v_pk_mul_f32 v[68:69], v[0:1], v[70:71] op_sel_hi:[0,1]
	v_pk_mul_f32 v[74:75], v[46:47], v[88:89] op_sel_hi:[0,1]
	v_pk_mul_f32 v[88:89], v[2:3], v[90:91] op_sel_hi:[0,1]
	v_pk_mul_f32 v[78:79], v[230:231], v[234:235]
	v_pk_mul_f32 v[76:77], v[228:229], v[232:233]
	v_pk_fma_f32 v[58:59], v[58:59], v[78:79], v[48:49]
	v_pk_fma_f32 v[56:57], v[56:57], v[76:77], v[92:93]
	v_pk_fma_f32 v[68:69], v[68:69], v[76:77], v[94:95]
	v_pk_fma_f32 v[70:71], v[72:73], v[78:79], v[96:97]
	v_pk_fma_f32 v[72:73], v[84:85], v[76:77], v[98:99]
	v_pk_fma_f32 v[74:75], v[74:75], v[78:79], v[100:101]
	v_pk_fma_f32 v[76:77], v[86:87], v[76:77], v[102:103]
	v_pk_fma_f32 v[78:79], v[88:89], v[78:79], v[64:65]
	global_store_dwordx4 v[28:29], v[56:59], off offset:2048 nt
	global_store_dwordx4 v[30:31], v[68:71], off offset:2048 nt
	global_store_dwordx4 v[32:33], v[72:75], off offset:2048 nt
	global_store_dwordx4 v[34:35], v[76:79], off offset:2048 nt
	s_nop 0
	v_lshlrev_b32_e32 v48, 16, v20
	v_and_b32_e32 v49, 0xffff0000, v20
	v_lshlrev_b32_e32 v20, 16, v21
	v_and_b32_e32 v21, 0xffff0000, v21
	v_lshlrev_b32_e32 v72, 16, v24
	v_and_b32_e32 v73, 0xffff0000, v24
	v_lshlrev_b32_e32 v74, 16, v25
	v_and_b32_e32 v75, 0xffff0000, v25
	v_lshlrev_b32_e32 v76, 16, v26
	v_and_b32_e32 v77, 0xffff0000, v26
	v_lshlrev_b32_e32 v78, 16, v27
	v_and_b32_e32 v79, 0xffff0000, v27
	v_pk_mul_f32 v[24:25], v[40:41], v[38:39] op_sel_hi:[0,1]
	v_pk_mul_f32 v[26:27], v[40:41], v[36:37] op_sel_hi:[0,1]
	v_pk_mul_f32 v[38:39], v[0:1], v[42:43] op_sel_hi:[0,1]
	v_pk_mul_f32 v[40:41], v[46:47], v[52:53] op_sel_hi:[0,1]
	v_pk_mul_f32 v[42:43], v[46:47], v[50:51] op_sel_hi:[0,1]
	v_lshlrev_b32_e32 v64, 16, v22
	v_and_b32_e32 v65, 0xffff0000, v22
	v_lshlrev_b32_e32 v22, 16, v23
	v_and_b32_e32 v23, 0xffff0000, v23
	v_pk_mul_f32 v[36:37], v[0:1], v[44:45] op_sel_hi:[0,1]
	v_pk_mul_f32 v[44:45], v[2:3], v[62:63] op_sel_hi:[0,1]
	v_pk_mul_f32 v[46:47], v[2:3], v[60:61] op_sel_hi:[0,1]
	v_pk_mul_f32 v[50:51], v[238:239], v[242:243]
	v_pk_mul_f32 v[52:53], v[236:237], v[240:241]
	v_pk_fma_f32 v[2:3], v[24:25], v[50:51], v[20:21]
	v_pk_fma_f32 v[0:1], v[26:27], v[52:53], v[48:49]
	v_pk_fma_f32 v[20:21], v[38:39], v[52:53], v[64:65]
	v_pk_fma_f32 v[22:23], v[36:37], v[50:51], v[22:23]
	v_pk_fma_f32 v[24:25], v[42:43], v[52:53], v[72:73]
	v_pk_fma_f32 v[26:27], v[40:41], v[50:51], v[74:75]
	v_pk_fma_f32 v[36:37], v[46:47], v[52:53], v[76:77]
	v_pk_fma_f32 v[38:39], v[44:45], v[50:51], v[78:79]
	global_store_dwordx4 v[28:29], v[0:3], off offset:3072 nt
	global_store_dwordx4 v[30:31], v[20:23], off offset:3072 nt
	global_store_dwordx4 v[32:33], v[24:27], off offset:3072 nt
	global_store_dwordx4 v[34:35], v[36:39], off offset:3072 nt
	s_cbranch_scc1 .LBB0_1103
